# attention loops: row-max half-wave exchange via v_permlane32_swap instead of ds_bpermute + lgkmcnt(0)
# speedup vs baseline: 1.0529x; 1.0529x over previous
; __device__ __forceinline__ void attn_tile(const LAS unsigned char* Kt, const LAS unsigned char* Vt, const LAS f32x4* ck, const bf16x8 (&qr)[4], const float cq2, const int kp0, const int qpos, const int qfirst, ...
;     ...
;             float rm = fmaxf(p0[0], p1[0]);
; #pragma unroll
;             for (int r = 1; r < 16; ++r) rm = fmaxf(rm, fmaxf(p0[r], p1[r]));
;             rm = fmaxf(rm, __shfl_xor(rm, 32));
;             if (first) { m_run = rm; cqm = cq2 - rm;
; #pragma unroll
;                 for (int r = 0; r < 16; ++r) { p0[r] -= rm; p1[r] -= rm; } }
;             else if (__any(rm > 8.f)) { const float dl = fmaxf(rm, 0.f), alpha = __builtin_amdgcn_exp2f(-dl); m_run += dl; cqm -= dl; l_run *= alpha;
; #pragma unroll
;                 for (int r = 0; r < 16; ++r) { p0[r] -= dl; p1[r] -= dl; o0[r] *= alpha; o1[r] *= alpha; } }
.LBB0_475:
	s_nop 10
	v_max_f32_e32 v1, v51, v51
	v_max_f32_e32 v185, v35, v35
	v_max_f32_e32 v1, v185, v1
	v_max_f32_e32 v185, v52, v52
	v_max_f32_e32 v186, v36, v36
	v_max_f32_e32 v185, v186, v185
	v_max_f32_e32 v186, v53, v53
	v_max_f32_e32 v187, v37, v37
	v_max3_f32 v1, v34, v50, v1
	v_max_f32_e32 v186, v187, v186
	v_max3_f32 v1, v1, v185, v186
	v_max_f32_e32 v185, v54, v54
	v_max_f32_e32 v186, v38, v38
	v_max_f32_e32 v185, v186, v185
	v_max_f32_e32 v186, v55, v55
	v_max_f32_e32 v187, v39, v39
	v_max_f32_e32 v186, v187, v186
	v_max3_f32 v1, v1, v185, v186
	v_max_f32_e32 v185, v56, v56
	v_max_f32_e32 v186, v40, v40
	v_max_f32_e32 v185, v186, v185
	v_max_f32_e32 v186, v57, v57
	v_max_f32_e32 v187, v41, v41
	v_max_f32_e32 v186, v187, v186
	v_max3_f32 v1, v1, v185, v186
	v_max_f32_e32 v185, v58, v58
	v_max_f32_e32 v186, v42, v42
	v_max_f32_e32 v185, v186, v185
	v_max_f32_e32 v186, v59, v59
	v_max_f32_e32 v187, v43, v43
	v_max_f32_e32 v186, v187, v186
	v_max3_f32 v1, v1, v185, v186
	v_max_f32_e32 v185, v60, v60
	v_max_f32_e32 v186, v44, v44
	v_max_f32_e32 v185, v186, v185
	v_max_f32_e32 v186, v61, v61
	v_max_f32_e32 v187, v45, v45
	v_max_f32_e32 v186, v187, v186
	v_max3_f32 v1, v1, v185, v186
	v_max_f32_e32 v185, v62, v62
	v_max_f32_e32 v186, v46, v46
	v_max_f32_e32 v185, v186, v185
	v_max_f32_e32 v186, v63, v63
	v_max_f32_e32 v187, v47, v47
	v_max_f32_e32 v186, v187, v186
	v_max3_f32 v1, v1, v185, v186
	v_max_f32_e32 v185, v64, v64
	v_max_f32_e32 v186, v48, v48
	v_max_f32_e32 v185, v186, v185
	v_max_f32_e32 v186, v65, v65
	v_max_f32_e32 v187, v49, v49
	v_max_f32_e32 v186, v187, v186
	v_max3_f32 v1, v1, v185, v186
	v_mov_b32_e32 v185, v1
	s_nop 1
	v_permlane32_swap_b32_e32 v1, v185
	v_max_f32_e32 v1, v1, v185
	s_and_saveexec_b64 s[0:1], vcc
	s_xor_b64 s[0:1], exec, s[0:1]
	s_cbranch_execz .LBB0_479
	s_mov_b32 s10, 0x41000000
	v_cmp_lt_f32_e32 vcc, s10, v1
	s_cbranch_vccz .LBB0_478
	v_max_f32_e32 v1, v1, v1
	v_max_f32_e32 v1, 0, v1
	v_exp_f32_e64 v186, -v1
	v_add_f32_e32 v139, v139, v1
	v_sub_f32_e32 v184, v184, v1
	v_sub_f32_e32 v49, v49, v1
	v_mul_f32_e32 v118, v118, v186
	v_sub_f32_e32 v48, v48, v1
	v_sub_f32_e32 v47, v47, v1
	v_sub_f32_e32 v46, v46, v1
	v_sub_f32_e32 v45, v45, v1
	v_sub_f32_e32 v44, v44, v1
	v_sub_f32_e32 v43, v43, v1
	v_sub_f32_e32 v42, v42, v1
	v_sub_f32_e32 v41, v41, v1
	v_sub_f32_e32 v40, v40, v1
	v_sub_f32_e32 v39, v39, v1
	v_sub_f32_e32 v38, v38, v1
	v_sub_f32_e32 v37, v37, v1
	v_sub_f32_e32 v36, v36, v1
	v_sub_f32_e32 v35, v35, v1
	v_sub_f32_e32 v34, v34, v1
	v_sub_f32_e32 v65, v65, v1
	v_sub_f32_e32 v64, v64, v1
	v_sub_f32_e32 v63, v63, v1
	v_sub_f32_e32 v62, v62, v1
	v_sub_f32_e32 v61, v61, v1
	v_sub_f32_e32 v60, v60, v1
	v_sub_f32_e32 v59, v59, v1
	v_sub_f32_e32 v58, v58, v1
	v_sub_f32_e32 v57, v57, v1
	v_sub_f32_e32 v56, v56, v1
	v_sub_f32_e32 v55, v55, v1
	v_sub_f32_e32 v54, v54, v1
	v_sub_f32_e32 v53, v53, v1
	v_sub_f32_e32 v52, v52, v1
	v_sub_f32_e32 v51, v51, v1
	v_sub_f32_e32 v50, v50, v1
	v_pk_mul_f32 v[32:33], v[32:33], v[186:187] op_sel_hi:[1,0]
	v_pk_mul_f32 v[30:31], v[30:31], v[186:187] op_sel_hi:[1,0]
	v_pk_mul_f32 v[28:29], v[28:29], v[186:187] op_sel_hi:[1,0]
	v_pk_mul_f32 v[26:27], v[26:27], v[186:187] op_sel_hi:[1,0]
	v_pk_mul_f32 v[24:25], v[24:25], v[186:187] op_sel_hi:[1,0]
	v_pk_mul_f32 v[22:23], v[22:23], v[186:187] op_sel_hi:[1,0]
	v_pk_mul_f32 v[20:21], v[20:21], v[186:187] op_sel_hi:[1,0]
	v_pk_mul_f32 v[18:19], v[18:19], v[186:187] op_sel_hi:[1,0]
	v_pk_mul_f32 v[16:17], v[16:17], v[186:187] op_sel_hi:[1,0]
	v_pk_mul_f32 v[14:15], v[14:15], v[186:187] op_sel_hi:[1,0]
	v_pk_mul_f32 v[12:13], v[12:13], v[186:187] op_sel_hi:[1,0]
	v_pk_mul_f32 v[10:11], v[10:11], v[186:187] op_sel_hi:[1,0]
	v_pk_mul_f32 v[8:9], v[8:9], v[186:187] op_sel_hi:[1,0]
	v_pk_mul_f32 v[6:7], v[6:7], v[186:187] op_sel_hi:[1,0]
	v_pk_mul_f32 v[4:5], v[4:5], v[186:187] op_sel_hi:[1,0]
	v_pk_mul_f32 v[2:3], v[2:3], v[186:187] op_sel_hi:[1,0]

; __device__ __forceinline__ void attn_tile(const LAS unsigned char* Kt, const LAS unsigned char* Vt, const LAS f32x4* ck, const bf16x8 (&qr)[4], const float cq2, const int kp0, const int qpos, const int qfirst, ...
;     ...
;             float rm = fmaxf(p0[0], p1[0]);
; #pragma unroll
;             for (int r = 1; r < 16; ++r) rm = fmaxf(rm, fmaxf(p0[r], p1[r]));
;             rm = fmaxf(rm, __shfl_xor(rm, 32));
;             if (first) { m_run = rm; cqm = cq2 - rm;
; #pragma unroll
;                 for (int r = 0; r < 16; ++r) { p0[r] -= rm; p1[r] -= rm; } }
;             else if (__any(rm > 8.f)) { const float dl = fmaxf(rm, 0.f), alpha = __builtin_amdgcn_exp2f(-dl); m_run += dl; cqm -= dl; l_run *= alpha;
; #pragma unroll
;                 for (int r = 0; r < 16; ++r) { p0[r] -= dl; p1[r] -= dl; o0[r] *= alpha; o1[r] *= alpha; } }
.LBB0_529:
	s_or_b64 exec, exec, s[10:11]
	s_nop 8
	v_max3_f32 v109, v34, v35, v36
	v_max3_f32 v109, v109, v37, v38
	v_max3_f32 v109, v109, v39, v40
	v_max3_f32 v109, v109, v41, v42
	v_max3_f32 v109, v109, v43, v44
	v_max3_f32 v109, v109, v45, v46
	v_max3_f32 v109, v109, v47, v48
	v_max3_f32 v110, v50, v51, v52
	v_max3_f32 v110, v110, v53, v54
	v_max3_f32 v110, v110, v55, v56
	v_max3_f32 v110, v110, v57, v58
	v_max3_f32 v110, v110, v59, v60
	v_max3_f32 v110, v110, v61, v62
	v_max3_f32 v110, v110, v63, v64
	v_max3_f32 v109, v109, v110, v49
	v_max_f32_e32 v109, v109, v65
	v_mov_b32_e32 v110, v109
	s_nop 1
	v_permlane32_swap_b32_e32 v109, v110
	v_max_f32_e32 v109, v109, v110
	s_and_saveexec_b64 s[0:1], vcc
	s_xor_b64 s[0:1], exec, s[0:1]
	s_cbranch_execz .LBB0_533
	s_mov_b32 s10, 0x41000000
	v_cmp_lt_f32_e32 vcc, s10, v109
	s_cbranch_vccz .LBB0_532
	v_max_f32_e32 v109, v109, v109
	v_max_f32_e32 v109, 0, v109
	v_exp_f32_e64 v110, -v109
	v_add_f32_e32 v108, v108, v109
	v_sub_f32_e32 v1, v1, v109
	v_sub_f32_e32 v49, v49, v109
	v_mul_f32_e32 v103, v103, v110
	v_sub_f32_e32 v48, v48, v109
	v_sub_f32_e32 v47, v47, v109
	v_sub_f32_e32 v46, v46, v109
	v_sub_f32_e32 v45, v45, v109
	v_sub_f32_e32 v44, v44, v109
	v_sub_f32_e32 v43, v43, v109
	v_sub_f32_e32 v42, v42, v109
	v_sub_f32_e32 v41, v41, v109
	v_sub_f32_e32 v40, v40, v109
	v_sub_f32_e32 v39, v39, v109
	v_sub_f32_e32 v38, v38, v109
	v_sub_f32_e32 v37, v37, v109
	v_sub_f32_e32 v36, v36, v109
	v_sub_f32_e32 v35, v35, v109
	v_sub_f32_e32 v34, v34, v109
	v_sub_f32_e32 v65, v65, v109
	v_sub_f32_e32 v64, v64, v109
	v_sub_f32_e32 v63, v63, v109
	v_sub_f32_e32 v62, v62, v109
	v_sub_f32_e32 v61, v61, v109
	v_sub_f32_e32 v60, v60, v109
	v_sub_f32_e32 v59, v59, v109
	v_sub_f32_e32 v58, v58, v109
	v_sub_f32_e32 v57, v57, v109
	v_sub_f32_e32 v56, v56, v109
	v_sub_f32_e32 v55, v55, v109
	v_sub_f32_e32 v54, v54, v109
	v_sub_f32_e32 v53, v53, v109
	v_sub_f32_e32 v52, v52, v109
	v_sub_f32_e32 v51, v51, v109
	v_sub_f32_e32 v50, v50, v109
	v_pk_mul_f32 v[32:33], v[32:33], v[110:111] op_sel_hi:[1,0]
	v_pk_mul_f32 v[30:31], v[30:31], v[110:111] op_sel_hi:[1,0]
	v_pk_mul_f32 v[28:29], v[28:29], v[110:111] op_sel_hi:[1,0]
	v_pk_mul_f32 v[26:27], v[26:27], v[110:111] op_sel_hi:[1,0]
	v_pk_mul_f32 v[24:25], v[24:25], v[110:111] op_sel_hi:[1,0]
	v_pk_mul_f32 v[22:23], v[22:23], v[110:111] op_sel_hi:[1,0]
	v_pk_mul_f32 v[20:21], v[20:21], v[110:111] op_sel_hi:[1,0]
	v_pk_mul_f32 v[18:19], v[18:19], v[110:111] op_sel_hi:[1,0]
	v_pk_mul_f32 v[16:17], v[16:17], v[110:111] op_sel_hi:[1,0]
	v_pk_mul_f32 v[14:15], v[14:15], v[110:111] op_sel_hi:[1,0]
	v_pk_mul_f32 v[12:13], v[12:13], v[110:111] op_sel_hi:[1,0]
	v_pk_mul_f32 v[10:11], v[10:11], v[110:111] op_sel_hi:[1,0]
	v_pk_mul_f32 v[8:9], v[8:9], v[110:111] op_sel_hi:[1,0]
	v_pk_mul_f32 v[6:7], v[6:7], v[110:111] op_sel_hi:[1,0]
	v_pk_mul_f32 v[4:5], v[4:5], v[110:111] op_sel_hi:[1,0]
	v_pk_mul_f32 v[2:3], v[2:3], v[110:111] op_sel_hi:[1,0]
